# GEMM phase prologue: all 14 cold stage loads (K-tiles 0 and 1) issued before the first wait (vmcnt(2)+barrier moved past the tile-1 loads as vmcnt(8))
# baseline (speedup 1.0000x reference)
; #define PG8_STAGE(bufoff, gbase, voff) do { _Pragma("unroll") for (int _i = 0; _i < 2; ++_i) \
;         __builtin_amdgcn_global_load_lds((const unsigned*)((const char*)(gbase) + (voff)[_i]), (PG8_LAS unsigned*)(lds + (bufoff) + ldsw + _i * 8192), 16, 0, 0); } while (0)
; #define PG8_WAIT_V(n) asm volatile("s_waitcnt vmcnt(" #n ")" ::: "memory")
; #define PG8_BAR __builtin_amdgcn_s_barrier()
; template <class Epi, class Sched, bool ALIGN_EPI = false, bool SP2 = false>
; __device__ __forceinline__ void gemm_phase(PG8_LAS unsigned char* lds, const Gemm g, const Sched& S, const Epi& E) {
;     ...
;         PG8_STAGE(PG8_SB(0, 0), cB, voffB); PG8_STAGE(PG8_SB(0, 1), cB + hstep, voffB); PG8_STAGE(PG8_SA(0, 0), cA, voffA); PG8_STAGE(PG8_SA(0, 1), cA + hstep, voffA);
;         if (wr == 1) PG8_BAR;
;         PG8_WAIT_V(2); PG8_BAR;
;         PG8_STAGE(PG8_SB(1, 0), cB + kstep, voffB); PG8_STAGE(PG8_SA(1, 0), cA + kstep, voffA); PG8_STAGE(PG8_SB(1, 1), cB + hstep + kstep, voffB);
;         PG8_WAIT_V(6); PG8_BAR;
.LBB0_85:
	s_add_u32 s16, s22, 0xd6e4000
	s_addc_u32 s17, s23, 0
	v_lshrrev_b32_e32 v18, 1, v16
	s_add_u32 s54, s33, 0x4000
	v_and_b32_e32 v18, 24, v18
	s_addc_u32 s55, s58, 0
	v_and_b32_e32 v17, 15, v16
	v_lshlrev_b32_e32 v19, 1, v18
	v_lshlrev_b32_e32 v16, 2, v16
	s_lshl_b32 s3, s3, 5
	v_lshl_or_b32 v162, s20, 6, v17
	v_lshl_or_b32 v17, v17, 6, v19
	s_lshl_b32 s20, s20, 13
	v_and_b32_e32 v16, 32, v16
	s_and_b32 s3, s3, 0x60
	s_add_i32 m0, s7, 0x18000
	v_lshl_add_u64 v[8:9], v[8:9], 0, s[10:11]
	v_bitop3_b32 v19, v17, s20, v16 bitop3:0xde
	s_lshl_b32 s20, s3, 7
	global_load_lds_dwordx4 v[8:9], off
	v_lshl_add_u64 v[6:7], v[6:7], 0, s[10:11]
	s_add_i32 m0, s7, 0x1a000
	s_add_i32 s56, s7, 0x8000
	s_add_i32 s57, s7, 0xa000
	global_load_lds_dwordx4 v[6:7], off
	v_lshl_add_u64 v[2:3], v[2:3], 0, s[10:11]
	s_mov_b32 m0, s56
	s_add_u32 s26, s24, 0x80080
	global_load_lds_dwordx4 v[2:3], off
	v_lshl_add_u64 v[2:3], v[4:5], 0, s[10:11]
	s_mov_b32 m0, s57
	s_addc_u32 s27, s25, 0
	global_load_lds_dwordx4 v[2:3], off
	s_add_i32 m0, s7, 0x1c000
	v_lshl_add_u64 v[2:3], s[26:27], 0, v[0:1]
	global_load_lds_dwordx4 v[2:3], off
	v_lshl_add_u64 v[2:3], s[26:27], 0, v[146:147]
	s_add_i32 m0, s7, 0x1e000
	s_cmpk_lt_u32 s2, 0x100
	global_load_lds_dwordx4 v[2:3], off
	s_waitcnt vmcnt(8)
	s_barrier
	v_lshlrev_b32_e32 v2, 15, v10
	v_and_b32_e32 v2, 0xffff0000, v2
	v_lshl_add_u32 v2, v11, 12, v2
	v_and_b32_e32 v3, 1, v10
	v_lshl_or_b32 v2, v3, 6, v2
	v_mov_b32_e32 v152, v227
	v_lshlrev_b32_e32 v2, 15, v14
	v_and_b32_e32 v2, 0xffff0000, v2
	s_waitcnt vmcnt(6)
	v_lshl_add_u32 v2, v13, 12, v2
	v_and_b32_e32 v3, 1, v14
	v_or_b32_e32 v164, s3, v18
	v_lshl_or_b32 v2, v3, 6, v2
	v_readlane_b32 s2, v252, 17
	v_mov_b32_e32 v163, v231
	s_cselect_b64 s[26:27], -1, 0
	v_mov_b32_e32 v153, v1
	v_mov_b32_e32 v154, v226
	v_mov_b32_e32 v155, v1
	s_mov_b32 s58, 0
	v_mov_b32_e32 v165, v230
	v_readlane_b32 s60, v252, 9
	s_mov_b32 s59, s2
	s_barrier
	v_readlane_b32 s3, v252, 18
	s_branch .LBB0_88

; #define PG8_STAGE(bufoff, gbase, voff) do { _Pragma("unroll") for (int _i = 0; _i < 2; ++_i) \
;         __builtin_amdgcn_global_load_lds((const unsigned*)((const char*)(gbase) + (voff)[_i]), (PG8_LAS unsigned*)(lds + (bufoff) + ldsw + _i * 8192), 16, 0, 0); } while (0)
; #define PG8_WAIT_V(n) asm volatile("s_waitcnt vmcnt(" #n ")" ::: "memory")
; #define PG8_BAR __builtin_amdgcn_s_barrier()
; template <class Epi, class Sched, bool ALIGN_EPI = false, bool SP2 = false>
; __device__ __forceinline__ void gemm_phase(PG8_LAS unsigned char* lds, const Gemm g, const Sched& S, const Epi& E) {
;     ...
;         PG8_STAGE(PG8_SB(0, 0), cB, voffB); PG8_STAGE(PG8_SB(0, 1), cB + hstep, voffB); PG8_STAGE(PG8_SA(0, 0), cA, voffA); PG8_STAGE(PG8_SA(0, 1), cA + hstep, voffA);
;         if (wr == 1) PG8_BAR;
;         PG8_WAIT_V(2); PG8_BAR;
;         PG8_STAGE(PG8_SB(1, 0), cB + kstep, voffB); PG8_STAGE(PG8_SA(1, 0), cA + kstep, voffA); PG8_STAGE(PG8_SB(1, 1), cB + hstep + kstep, voffB);
;         PG8_WAIT_V(6); PG8_BAR;
.LBB0_303:
	s_add_u32 s44, s22, 0xd6e4000
	s_addc_u32 s45, s23, 0
	s_add_u32 s46, s22, 0x116e4000
	s_addc_u32 s47, s23, 0
	v_bfe_u32 v17, v15, 4, 2
	s_add_u32 s48, s22, 0x92e4000
	v_and_b32_e32 v16, 15, v15
	v_lshlrev_b32_e32 v19, 4, v17
	v_lshlrev_b32_e32 v15, 2, v15
	s_addc_u32 s49, s23, 0
	s_and_b32 s73, s4, 3
	v_lshl_or_b32 v150, s3, 6, v16
	v_lshl_or_b32 v16, v16, 6, v19
	s_lshl_b32 s3, s3, 13
	v_and_b32_e32 v15, 32, v15
	s_add_i32 m0, s65, 0x18000
	v_lshl_add_u64 v[8:9], v[8:9], 0, s[10:11]
	v_bitop3_b32 v19, v16, s3, v15 bitop3:0xde
	s_lshl_b32 s3, s73, 12
	global_load_lds_dwordx4 v[8:9], off
	v_lshl_add_u64 v[6:7], v[6:7], 0, s[10:11]
	s_add_i32 m0, s65, 0x1a000
	s_add_i32 s86, s65, 0x8000
	s_add_i32 s87, s65, 0xa000
	global_load_lds_dwordx4 v[6:7], off
	v_lshl_add_u64 v[2:3], v[2:3], 0, s[10:11]
	s_mov_b32 m0, s86
	s_add_u32 s4, s12, 0x80080
	global_load_lds_dwordx4 v[2:3], off
	v_lshl_add_u64 v[2:3], v[4:5], 0, s[10:11]
	s_mov_b32 m0, s87
	s_addc_u32 s5, s13, 0
	global_load_lds_dwordx4 v[2:3], off
	s_add_i32 m0, s65, 0x1c000
	v_lshl_add_u64 v[2:3], s[4:5], 0, v[134:135]
	global_load_lds_dwordx4 v[2:3], off
	v_lshl_add_u64 v[2:3], s[4:5], 0, v[130:131]
	s_add_i32 m0, s65, 0x1e000
	v_lshlrev_b32_e32 v18, 3, v17
	global_load_lds_dwordx4 v[2:3], off
	s_waitcnt vmcnt(8)
	s_barrier
	v_lshlrev_b32_e32 v2, 15, v0
	v_and_b32_e32 v2, 0xffff0000, v2
	v_lshl_add_u32 v2, v10, 12, v2
	v_and_b32_e32 v0, 1, v0
	v_lshl_or_b32 v0, v0, 6, v2
	v_mov_b32_e32 v138, v227
	v_lshlrev_b32_e32 v0, 15, v13
	v_and_b32_e32 v0, 0xffff0000, v0
	s_waitcnt vmcnt(6)
	v_lshl_add_u32 v0, v12, 12, v0
	v_and_b32_e32 v2, 1, v13
	v_mov_b32_e32 v151, v231
	s_cmpk_lt_u32 s2, 0x100
	v_lshl_or_b32 v0, v2, 6, v0
	v_readlane_b32 s2, v252, 21
	s_cselect_b64 s[50:51], -1, 0
	s_mov_b32 s88, 0
	v_cmp_eq_u32_e64 s[40:41], 0, v17
	v_lshl_or_b32 v152, s73, 5, v18
	v_mov_b32_e32 v139, v1
	v_mov_b32_e32 v140, v226
	v_mov_b32_e32 v141, v1
	v_mov_b32_e32 v153, v230
	v_readlane_b32 s89, v252, 4
	s_mov_b32 s4, s2
	s_barrier
	v_readlane_b32 s3, v252, 22
	s_branch .LBB0_306

; #define PG8_STAGE(bufoff, gbase, voff) do { _Pragma("unroll") for (int _i = 0; _i < 2; ++_i) \
;         __builtin_amdgcn_global_load_lds((const unsigned*)((const char*)(gbase) + (voff)[_i]), (PG8_LAS unsigned*)(lds + (bufoff) + ldsw + _i * 8192), 16, 0, 0); } while (0)
; #define PG8_WAIT_V(n) asm volatile("s_waitcnt vmcnt(" #n ")" ::: "memory")
; #define PG8_BAR __builtin_amdgcn_s_barrier()
; template <class Epi, class Sched, bool ALIGN_EPI = false, bool SP2 = false>
; __device__ __forceinline__ void gemm_phase(PG8_LAS unsigned char* lds, const Gemm g, const Sched& S, const Epi& E) {
;     ...
;         PG8_STAGE(PG8_SB(0, 0), cB, voffB); PG8_STAGE(PG8_SB(0, 1), cB + hstep, voffB); PG8_STAGE(PG8_SA(0, 0), cA, voffA); PG8_STAGE(PG8_SA(0, 1), cA + hstep, voffA);
;         if (wr == 1) PG8_BAR;
;         PG8_WAIT_V(2); PG8_BAR;
;         PG8_STAGE(PG8_SB(1, 0), cB + kstep, voffB); PG8_STAGE(PG8_SA(1, 0), cA + kstep, voffA); PG8_STAGE(PG8_SB(1, 1), cB + hstep + kstep, voffB);
;         PG8_WAIT_V(6); PG8_BAR;
.LBB0_341:
	v_lshrrev_b32_e32 v17, 1, v0
	v_and_b32_e32 v17, 24, v17
	v_and_b32_e32 v16, 15, v0
	v_lshlrev_b32_e32 v18, 1, v17
	v_lshlrev_b32_e32 v0, 2, v0
	s_and_b32 s6, s3, 3
	v_lshl_or_b32 v168, s4, 6, v16
	v_lshl_or_b32 v16, v16, 6, v18
	s_lshl_b32 s4, s4, 13
	v_and_b32_e32 v0, 32, v0
	s_add_i32 m0, s58, 0x18000
	v_lshl_add_u64 v[8:9], v[8:9], 0, s[10:11]
	v_bitop3_b32 v18, v16, s4, v0 bitop3:0xde
	s_lshl_b32 s7, s6, 5
	s_lshl_b32 s4, s6, 12
	global_load_lds_dwordx4 v[8:9], off
	v_lshl_add_u64 v[6:7], v[6:7], 0, s[10:11]
	s_add_i32 m0, s58, 0x1a000
	s_add_i32 s64, s58, 0x8000
	s_add_i32 s65, s58, 0xa000
	v_mov_b32_e32 v169, v231
	global_load_lds_dwordx4 v[6:7], off
	v_lshl_add_u64 v[2:3], v[2:3], 0, s[10:11]
	s_mov_b32 m0, s64
	s_add_u32 s4, s12, 0x80080
	global_load_lds_dwordx4 v[2:3], off
	v_lshl_add_u64 v[2:3], v[4:5], 0, s[10:11]
	s_mov_b32 m0, s65
	s_addc_u32 s5, s13, 0
	global_load_lds_dwordx4 v[2:3], off
	s_add_i32 m0, s58, 0x1c000
	v_lshl_add_u64 v[2:3], s[4:5], 0, v[150:151]
	global_load_lds_dwordx4 v[2:3], off
	v_lshl_add_u64 v[2:3], s[4:5], 0, v[146:147]
	s_add_i32 m0, s58, 0x1e000
	s_cmpk_lt_u32 s2, 0x100
	global_load_lds_dwordx4 v[2:3], off
	s_waitcnt vmcnt(8)
	s_barrier
	v_and_or_b32 v2, s7, 32, v17
	v_lshlrev_b32_e32 v0, 2, v2
	v_lshl_add_u64 v[4:5], s[22:23], 0, v[0:1]
	v_lshlrev_b32_e32 v0, 15, v10
	v_and_b32_e32 v0, 0xffff0000, v0
	s_cselect_b64 s[26:27], -1, 0
	s_cmp_gt_u32 s6, 1
	v_lshl_add_u32 v0, v11, 12, v0
	v_and_b32_e32 v3, 1, v10
	s_cselect_b64 s[44:45], -1, 0
	s_bfe_u32 s66, s3, 0x10001
	s_mov_b64 s[2:3], 0x90e4000
	v_lshl_or_b32 v0, v3, 6, v0
	v_lshl_add_u64 v[154:155], v[4:5], 0, s[2:3]
	s_mov_b64 s[2:3], 0x91e4000
	v_mov_b32_e32 v158, v227
	v_lshlrev_b32_e32 v0, 15, v14
	s_cmp_lt_u32 s6, 2
	v_lshl_add_u64 v[156:157], v[4:5], 0, s[2:3]
	s_mov_b32 s2, 0x176e4000
	v_and_b32_e32 v0, 0xffff0000, v0
	s_waitcnt vmcnt(6)
	s_cselect_b32 s2, 0x156e4000, s2
	v_lshl_add_u32 v0, v13, 12, v0
	v_and_b32_e32 v3, 1, v14
	s_add_u32 s46, s22, s2
	v_lshl_or_b32 v0, v3, 6, v0
	v_readlane_b32 s2, v252, 25
	v_or_b32_e32 v170, 0xfffffc00, v2
	s_mov_b32 s67, 0
	s_addc_u32 s47, s23, 0
	v_or_b32_e32 v171, s7, v17
	v_mov_b32_e32 v159, v1
	v_mov_b32_e32 v160, v226
	v_mov_b32_e32 v161, v1
	v_mov_b32_e32 v172, v230
	v_lshlrev_b32_e32 v162, 1, v2
	v_readlane_b32 s72, v252, 14
	s_mov_b32 s4, s2
	s_barrier
	v_readlane_b32 s3, v252, 26
	s_branch .LBB0_344
